# final candidate: fast grid barrier + interleaved/peeled GEMM k-loops + pipelined B1 LDS reads (fwd-subst, row-norm)
# baseline (speedup 1.0000x reference)
; DI void phaseB1(const Params& p, int l, char* smem) {
;     ...
;     if (tid < 128) {
;       const int row = tid & 63, which = tid >> 6;
;       const float* src = which ? ks : qs;
;       float ss = 0.f;
;       for (int c0 = 0; c0 < 128; ++c0) { const int c = (c0 + row) & 127; const float v = src[row * 132 + c]; ss += v * v; }
;       float rr = rsqrtf(ss + 1e-6f);
;       if (which) rk[row] = rr; else rq[row] = rr * 0.08838834764831845f;
.LBB0_1857:
	v_add_u32_e32 v2, s3, v172
	v_and_b32_e32 v146, 0x7f, v2
	v_lshl_add_u32 v146, v146, 2, v181
	ds_read_b32 v146, v146
	v_add_u32_e32 v147, 1, v2
	v_and_b32_e32 v147, 0x7f, v147
	v_lshl_add_u32 v147, v147, 2, v181
	ds_read_b32 v147, v147
	v_add_u32_e32 v148, 2, v2
	v_and_b32_e32 v148, 0x7f, v148
	v_lshl_add_u32 v148, v148, 2, v181
	ds_read_b32 v148, v148
	v_add_u32_e32 v149, 3, v2
	v_and_b32_e32 v149, 0x7f, v149
	v_lshl_add_u32 v149, v149, 2, v181
	ds_read_b32 v149, v149
	v_add_u32_e32 v150, 4, v2
	v_and_b32_e32 v150, 0x7f, v150
	v_lshl_add_u32 v150, v150, 2, v181
	ds_read_b32 v150, v150
	v_add_u32_e32 v151, 5, v2
	v_and_b32_e32 v151, 0x7f, v151
	v_lshl_add_u32 v151, v151, 2, v181
	ds_read_b32 v151, v151
	v_add_u32_e32 v152, 6, v2
	v_and_b32_e32 v152, 0x7f, v152
	v_lshl_add_u32 v152, v152, 2, v181
	ds_read_b32 v152, v152
	v_add_u32_e32 v153, 7, v2
	v_and_b32_e32 v153, 0x7f, v153
	v_lshl_add_u32 v153, v153, 2, v181
	ds_read_b32 v153, v153
	s_waitcnt lgkmcnt(7)
	v_fmac_f32_e32 v0, v146, v146
	s_waitcnt lgkmcnt(6)
	v_fmac_f32_e32 v0, v147, v147
	s_waitcnt lgkmcnt(5)
	v_fmac_f32_e32 v0, v148, v148
	s_waitcnt lgkmcnt(4)
	v_fmac_f32_e32 v0, v149, v149
	s_waitcnt lgkmcnt(3)
	v_fmac_f32_e32 v0, v150, v150
	s_waitcnt lgkmcnt(2)
	v_fmac_f32_e32 v0, v151, v151
	s_waitcnt lgkmcnt(1)
	v_fmac_f32_e32 v0, v152, v152
	s_waitcnt lgkmcnt(0)
	v_fmac_f32_e32 v0, v153, v153
	v_add_u32_e32 v146, 8, v2
	v_and_b32_e32 v146, 0x7f, v146
	v_lshl_add_u32 v146, v146, 2, v181
	ds_read_b32 v146, v146
	v_add_u32_e32 v147, 9, v2
	v_and_b32_e32 v147, 0x7f, v147
	v_lshl_add_u32 v147, v147, 2, v181
	ds_read_b32 v147, v147
	v_add_u32_e32 v148, 10, v2
	v_and_b32_e32 v148, 0x7f, v148
	v_lshl_add_u32 v148, v148, 2, v181
	ds_read_b32 v148, v148
	v_add_u32_e32 v149, 11, v2
	v_and_b32_e32 v149, 0x7f, v149
	v_lshl_add_u32 v149, v149, 2, v181
	ds_read_b32 v149, v149
	v_add_u32_e32 v150, 12, v2
	v_and_b32_e32 v150, 0x7f, v150
	v_lshl_add_u32 v150, v150, 2, v181
	ds_read_b32 v150, v150
	v_add_u32_e32 v151, 13, v2
	v_and_b32_e32 v151, 0x7f, v151
	v_lshl_add_u32 v151, v151, 2, v181
	ds_read_b32 v151, v151
	v_add_u32_e32 v152, 14, v2
	v_and_b32_e32 v152, 0x7f, v152
	v_lshl_add_u32 v152, v152, 2, v181
	ds_read_b32 v152, v152
	v_add_u32_e32 v153, 15, v2
	v_and_b32_e32 v153, 0x7f, v153
	v_lshl_add_u32 v153, v153, 2, v181
	ds_read_b32 v153, v153
	s_add_i32 s3, s3, 16
	s_cmpk_eq_i32 s3, 0x80
	s_waitcnt lgkmcnt(7)
	v_fmac_f32_e32 v0, v146, v146
	s_waitcnt lgkmcnt(6)
	v_fmac_f32_e32 v0, v147, v147
	s_waitcnt lgkmcnt(5)
	v_fmac_f32_e32 v0, v148, v148
	s_waitcnt lgkmcnt(4)
	v_fmac_f32_e32 v0, v149, v149
	s_waitcnt lgkmcnt(3)
	v_fmac_f32_e32 v0, v150, v150
	s_waitcnt lgkmcnt(2)
	v_fmac_f32_e32 v0, v151, v151
	s_waitcnt lgkmcnt(1)
	v_fmac_f32_e32 v0, v152, v152
	s_waitcnt lgkmcnt(0)
	v_fmac_f32_e32 v0, v153, v153
	s_cbranch_scc0 .LBB0_1857
	v_add_f32_e32 v0, 0x358637bd, v0
	s_mov_b32 s3, 0x800000
	v_mul_f32_e32 v2, 0x4b800000, v0
	v_cmp_gt_f32_e32 vcc, s3, v0
	s_nop 1
	v_cndmask_b32_e32 v0, v0, v2, vcc
	v_rsq_f32_e32 v0, v0
	s_nop 0
	v_mul_f32_e32 v2, 0x45800000, v0
	v_cndmask_b32_e32 v0, v0, v2, vcc
	s_and_saveexec_b64 s[8:9], s[10:11]
	s_xor_b64 s[8:9], exec, s[8:9]
	ds_write_b32 v182, v0
	s_andn2_saveexec_b64 s[8:9], s[8:9]
	v_mul_f32_e32 v0, 0x3db504f3, v0
	ds_write_b32 v183, v0
	s_or_b64 exec, exec, s[8:9]
